# P1 K-loop: the compiler's conservative s_waitcnt vmcnt(0) at the top of every iteration removed (no VGPR-returning load is pending there); on top of peel + relaxed first-iteration waits
# baseline (speedup 1.0000x reference)
.LBB0_201:
	s_ashr_i32 s75, s74, 31
	s_lshl_b64 s[2:3], s[74:75], 19
	s_add_u32 s76, s60, s2
	s_addc_u32 s77, s61, s3
	s_and_b64 s[2:3], s[8:9], exec
	s_cselect_b32 s1, s77, s13
	s_cselect_b32 s2, s76, s12
	s_ashr_i32 s73, s72, 31
	s_lshl_b64 s[34:35], s[72:73], 19
	s_add_u32 s78, s36, s34
	s_addc_u32 s79, s37, s35
	s_and_b64 s[34:35], s[8:9], exec
	s_cselect_b32 s3, s79, s81
	s_cselect_b32 s34, s78, s80
	s_add_u32 s12, s12, 0x40080
	s_addc_u32 s13, s13, 0
	s_add_u32 s35, s80, 0x100
	s_addc_u32 s66, s81, 0
	s_mov_b32 s68, -2
	ds_read_b128 v[112:115], v218
	ds_read_b128 v[116:119], v218 offset:1024
	ds_read_b128 v[120:123], v218 offset:2048
	ds_read_b128 v[124:127], v218 offset:3072
	ds_read_b128 v[128:131], v219
	ds_read_b128 v[132:135], v219 offset:1024
	ds_read_b128 v[136:139], v219 offset:2048
	ds_read_b128 v[140:143], v219 offset:3072
	s_add_u32 s69, s12, 0xfffc0080
	s_addc_u32 s73, s13, -1
	s_cmp_eq_u32 s68, 12
	s_cselect_b32 s83, s1, s73
	s_cselect_b32 s82, s2, s69
	s_cselect_b32 s81, s3, s66
	s_cselect_b32 s80, s34, s35
	v_lshl_add_u64 v[230:231], s[12:13], 0, v[192:193]
	s_add_i32 m0, s15, 0xc000
	ds_read_b128 v[152:155], v220
	ds_read_b128 v[156:159], v220 offset:1024
	ds_read_b128 v[160:163], v220 offset:2048
	ds_read_b128 v[164:167], v220 offset:3072
	ds_read_b128 v[200:203], v220 offset:4096
	ds_read_b128 v[204:207], v220 offset:5120
	ds_read_b128 v[208:211], v220 offset:6144
	ds_read_b128 v[226:229], v220 offset:7168
	global_load_lds_dwordx4 v[230:231], off
	v_lshl_add_u64 v[230:231], s[12:13], 0, v[194:195]
	s_add_i32 m0, s15, 0xe000
	s_nop 0
	global_load_lds_dwordx4 v[230:231], off
	s_cmp_eq_u32 s98, 0
	s_cbranch_scc1 .Lrx0_0n
	s_waitcnt vmcnt(16)
	s_branch .Lrx0_0j

.LBB0_202:
	ds_read_b128 v[112:115], v218
	ds_read_b128 v[116:119], v218 offset:1024
	ds_read_b128 v[120:123], v218 offset:2048
	ds_read_b128 v[124:127], v218 offset:3072
	ds_read_b128 v[128:131], v219
	ds_read_b128 v[132:135], v219 offset:1024
	ds_read_b128 v[136:139], v219 offset:2048
	ds_read_b128 v[140:143], v219 offset:3072
	s_add_u32 s69, s12, 0xfffc0080
	s_addc_u32 s73, s13, -1
	s_cmp_eq_u32 s68, 12
	s_cselect_b32 s83, s1, s73
	s_cselect_b32 s82, s2, s69
	s_cselect_b32 s81, s3, s66
	s_cselect_b32 s80, s34, s35
	v_lshl_add_u64 v[230:231], s[12:13], 0, v[192:193]
	s_add_i32 m0, s15, 0xc000
	ds_read_b128 v[152:155], v220
	ds_read_b128 v[156:159], v220 offset:1024
	ds_read_b128 v[160:163], v220 offset:2048
	ds_read_b128 v[164:167], v220 offset:3072
	ds_read_b128 v[200:203], v220 offset:4096
	ds_read_b128 v[204:207], v220 offset:5120
	ds_read_b128 v[208:211], v220 offset:6144
	ds_read_b128 v[226:229], v220 offset:7168
	global_load_lds_dwordx4 v[230:231], off
	v_lshl_add_u64 v[230:231], s[12:13], 0, v[194:195]
	s_add_i32 m0, s15, 0xe000
	s_nop 0
	global_load_lds_dwordx4 v[230:231], off
	s_waitcnt vmcnt(8)
	s_waitcnt lgkmcnt(0)
	s_barrier
	s_setprio 1
	s_waitcnt lgkmcnt(0)
	v_mfma_f32_16x16x32_bf16 v[172:175], v[112:115], v[152:155], v[172:175]
	v_mfma_f32_16x16x32_bf16 v[172:175], v[116:119], v[156:159], v[172:175]
	v_mfma_f32_16x16x32_bf16 v[168:171], v[120:123], v[152:155], v[168:171]
	v_mfma_f32_16x16x32_bf16 v[168:171], v[124:127], v[156:159], v[168:171]
	v_mfma_f32_16x16x32_bf16 v[104:107], v[120:123], v[160:163], v[104:107]
	v_mfma_f32_16x16x32_bf16 v[104:107], v[124:127], v[164:167], v[104:107]
	v_mfma_f32_16x16x32_bf16 v[108:111], v[112:115], v[160:163], v[108:111]
	v_mfma_f32_16x16x32_bf16 v[108:111], v[116:119], v[164:167], v[108:111]
	v_mfma_f32_16x16x32_bf16 v[92:95], v[112:115], v[200:203], v[92:95]
	v_mfma_f32_16x16x32_bf16 v[92:95], v[116:119], v[204:207], v[92:95]
	v_mfma_f32_16x16x32_bf16 v[88:91], v[120:123], v[200:203], v[88:91]
	v_mfma_f32_16x16x32_bf16 v[88:91], v[124:127], v[204:207], v[88:91]
	v_mfma_f32_16x16x32_bf16 v[72:75], v[120:123], v[208:211], v[72:75]
	v_mfma_f32_16x16x32_bf16 v[72:75], v[124:127], v[226:229], v[72:75]
	v_mfma_f32_16x16x32_bf16 v[76:79], v[112:115], v[208:211], v[76:79]
	v_mfma_f32_16x16x32_bf16 v[76:79], v[116:119], v[226:229], v[76:79]
	s_setprio 0
	s_setprio 1
	v_mfma_f32_16x16x32_bf16 v[148:151], v[128:131], v[152:155], v[148:151]
	v_mfma_f32_16x16x32_bf16 v[148:151], v[132:135], v[156:159], v[148:151]
	v_mfma_f32_16x16x32_bf16 v[144:147], v[136:139], v[152:155], v[144:147]
	v_mfma_f32_16x16x32_bf16 v[144:147], v[140:143], v[156:159], v[144:147]
	v_mfma_f32_16x16x32_bf16 v[96:99], v[136:139], v[160:163], v[96:99]
	v_mfma_f32_16x16x32_bf16 v[96:99], v[140:143], v[164:167], v[96:99]
	v_mfma_f32_16x16x32_bf16 v[100:103], v[128:131], v[160:163], v[100:103]
	v_mfma_f32_16x16x32_bf16 v[100:103], v[132:135], v[164:167], v[100:103]
	v_mfma_f32_16x16x32_bf16 v[84:87], v[128:131], v[200:203], v[84:87]
	v_mfma_f32_16x16x32_bf16 v[84:87], v[132:135], v[204:207], v[84:87]
	v_mfma_f32_16x16x32_bf16 v[80:83], v[136:139], v[200:203], v[80:83]
	v_mfma_f32_16x16x32_bf16 v[80:83], v[140:143], v[204:207], v[80:83]
	v_mfma_f32_16x16x32_bf16 v[64:67], v[136:139], v[208:211], v[64:67]
	v_mfma_f32_16x16x32_bf16 v[64:67], v[140:143], v[226:229], v[64:67]
	v_mfma_f32_16x16x32_bf16 v[68:71], v[128:131], v[208:211], v[68:71]
	v_mfma_f32_16x16x32_bf16 v[68:71], v[132:135], v[226:229], v[68:71]
	s_setprio 0
	s_barrier
	s_add_i32 s69, s59, s14
	v_lshl_add_u64 v[230:231], s[80:81], 0, v[178:179]
	s_mov_b32 m0, s69
	ds_read_b128 v[152:155], v220 offset:16384
	ds_read_b128 v[156:159], v220 offset:17408
	ds_read_b128 v[160:163], v220 offset:18432
	ds_read_b128 v[164:167], v220 offset:19456
	ds_read_b128 v[200:203], v220 offset:20480
	ds_read_b128 v[204:207], v220 offset:21504
	ds_read_b128 v[208:211], v220 offset:22528
	ds_read_b128 v[226:229], v220 offset:23552
	global_load_lds_dwordx4 v[230:231], off
	s_add_i32 m0, s69, 0x2000
	s_add_u32 s86, s80, 0x40000
	v_lshl_add_u64 v[232:233], s[80:81], 0, v[182:183]
	s_addc_u32 s87, s81, 0
	s_add_i32 s69, s65, s14
	global_load_lds_dwordx4 v[232:233], off
	v_lshl_add_u64 v[234:235], s[86:87], 0, v[178:179]
	s_mov_b32 m0, s69
	v_lshl_add_u64 v[236:237], s[82:83], 0, v[180:181]
	global_load_lds_dwordx4 v[234:235], off
	v_lshl_add_u64 v[234:235], s[86:87], 0, v[182:183]
	s_add_i32 m0, s69, 0x2000
	s_nop 0
	global_load_lds_dwordx4 v[234:235], off
	v_lshl_add_u64 v[234:235], s[82:83], 0, v[176:177]
	s_mov_b32 m0, s15
	s_nop 0
	global_load_lds_dwordx4 v[234:235], off
	s_mov_b32 m0, s52
	s_nop 0
	global_load_lds_dwordx4 v[236:237], off
	s_waitcnt vmcnt(8)
	s_waitcnt lgkmcnt(0)
	s_barrier
	s_setprio 1
	s_waitcnt lgkmcnt(0)
	v_mfma_f32_16x16x32_bf16 v[60:63], v[112:115], v[152:155], v[60:63]
	v_mfma_f32_16x16x32_bf16 v[60:63], v[116:119], v[156:159], v[60:63]
	v_mfma_f32_16x16x32_bf16 v[56:59], v[120:123], v[152:155], v[56:59]
	v_mfma_f32_16x16x32_bf16 v[56:59], v[124:127], v[156:159], v[56:59]
	v_mfma_f32_16x16x32_bf16 v[40:43], v[120:123], v[160:163], v[40:43]
	v_mfma_f32_16x16x32_bf16 v[40:43], v[124:127], v[164:167], v[40:43]
	v_mfma_f32_16x16x32_bf16 v[44:47], v[112:115], v[160:163], v[44:47]
	v_mfma_f32_16x16x32_bf16 v[44:47], v[116:119], v[164:167], v[44:47]
	v_mfma_f32_16x16x32_bf16 v[28:31], v[112:115], v[200:203], v[28:31]
	v_mfma_f32_16x16x32_bf16 v[28:31], v[116:119], v[204:207], v[28:31]
	v_mfma_f32_16x16x32_bf16 v[24:27], v[120:123], v[200:203], v[24:27]
	v_mfma_f32_16x16x32_bf16 v[24:27], v[124:127], v[204:207], v[24:27]
	v_mfma_f32_16x16x32_bf16 v[8:11], v[120:123], v[208:211], v[8:11]
	v_mfma_f32_16x16x32_bf16 v[8:11], v[124:127], v[226:229], v[8:11]
	v_mfma_f32_16x16x32_bf16 v[12:15], v[112:115], v[208:211], v[12:15]
	v_mfma_f32_16x16x32_bf16 v[12:15], v[116:119], v[226:229], v[12:15]
	s_setprio 0
	s_setprio 1
	v_mfma_f32_16x16x32_bf16 v[52:55], v[128:131], v[152:155], v[52:55]
	v_mfma_f32_16x16x32_bf16 v[52:55], v[132:135], v[156:159], v[52:55]
	v_mfma_f32_16x16x32_bf16 v[48:51], v[136:139], v[152:155], v[48:51]
	v_mfma_f32_16x16x32_bf16 v[48:51], v[140:143], v[156:159], v[48:51]
	v_mfma_f32_16x16x32_bf16 v[32:35], v[136:139], v[160:163], v[32:35]
	v_mfma_f32_16x16x32_bf16 v[32:35], v[140:143], v[164:167], v[32:35]
	v_mfma_f32_16x16x32_bf16 v[36:39], v[128:131], v[160:163], v[36:39]
	v_mfma_f32_16x16x32_bf16 v[36:39], v[132:135], v[164:167], v[36:39]
	v_mfma_f32_16x16x32_bf16 v[20:23], v[128:131], v[200:203], v[20:23]
	v_mfma_f32_16x16x32_bf16 v[20:23], v[132:135], v[204:207], v[20:23]
	v_mfma_f32_16x16x32_bf16 v[16:19], v[136:139], v[200:203], v[16:19]
	v_mfma_f32_16x16x32_bf16 v[16:19], v[140:143], v[204:207], v[16:19]
	v_mfma_f32_16x16x32_bf16 v[0:3], v[136:139], v[208:211], v[0:3]
	v_mfma_f32_16x16x32_bf16 v[0:3], v[140:143], v[226:229], v[0:3]
	v_mfma_f32_16x16x32_bf16 v[4:7], v[128:131], v[208:211], v[4:7]
	v_mfma_f32_16x16x32_bf16 v[4:7], v[132:135], v[226:229], v[4:7]
	s_setprio 0
	s_barrier
	s_add_i32 s69, 0, 0x18000
	s_add_i32 s73, 0, 0x1c000
	v_add_u32_e32 v124, s69, v212
	v_add_u32_e32 v140, s73, v212
	ds_read_b128 v[112:115], v124
	ds_read_b128 v[116:119], v124 offset:1024
	ds_read_b128 v[120:123], v124 offset:2048
	ds_read_b128 v[124:127], v124 offset:3072
	ds_read_b128 v[128:131], v140
	ds_read_b128 v[132:135], v140 offset:1024
	ds_read_b128 v[136:139], v140 offset:2048
	ds_read_b128 v[140:143], v140 offset:3072
	s_add_u32 s82, s82, 0x40000
	s_addc_u32 s83, s83, 0
	s_mov_b32 m0, s53
	v_lshl_add_u64 v[238:239], s[82:83], 0, v[176:177]
	ds_read_b128 v[152:155], v220 offset:32768
	ds_read_b128 v[156:159], v220 offset:33792
	ds_read_b128 v[160:163], v220 offset:34816
	ds_read_b128 v[164:167], v220 offset:35840
	ds_read_b128 v[200:203], v220 offset:36864
	ds_read_b128 v[204:207], v220 offset:37888
	ds_read_b128 v[208:211], v220 offset:38912
	ds_read_b128 v[226:229], v220 offset:39936
	global_load_lds_dwordx4 v[238:239], off
	v_lshl_add_u64 v[238:239], s[82:83], 0, v[180:181]
	s_mov_b32 m0, s54
	s_nop 0
	global_load_lds_dwordx4 v[238:239], off
	s_waitcnt vmcnt(8)
	s_waitcnt lgkmcnt(0)
	s_barrier
	s_setprio 1
	s_waitcnt lgkmcnt(0)
	v_mfma_f32_16x16x32_bf16 v[172:175], v[112:115], v[152:155], v[172:175]
	v_mfma_f32_16x16x32_bf16 v[172:175], v[116:119], v[156:159], v[172:175]
	v_mfma_f32_16x16x32_bf16 v[168:171], v[120:123], v[152:155], v[168:171]
	v_mfma_f32_16x16x32_bf16 v[168:171], v[124:127], v[156:159], v[168:171]
	v_mfma_f32_16x16x32_bf16 v[104:107], v[120:123], v[160:163], v[104:107]
	v_mfma_f32_16x16x32_bf16 v[104:107], v[124:127], v[164:167], v[104:107]
	v_mfma_f32_16x16x32_bf16 v[108:111], v[112:115], v[160:163], v[108:111]
	v_mfma_f32_16x16x32_bf16 v[108:111], v[116:119], v[164:167], v[108:111]
	v_mfma_f32_16x16x32_bf16 v[92:95], v[112:115], v[200:203], v[92:95]
	v_mfma_f32_16x16x32_bf16 v[92:95], v[116:119], v[204:207], v[92:95]
	v_mfma_f32_16x16x32_bf16 v[88:91], v[120:123], v[200:203], v[88:91]
	v_mfma_f32_16x16x32_bf16 v[88:91], v[124:127], v[204:207], v[88:91]
	v_mfma_f32_16x16x32_bf16 v[72:75], v[120:123], v[208:211], v[72:75]
	v_mfma_f32_16x16x32_bf16 v[72:75], v[124:127], v[226:229], v[72:75]
	v_mfma_f32_16x16x32_bf16 v[76:79], v[112:115], v[208:211], v[76:79]
	v_mfma_f32_16x16x32_bf16 v[76:79], v[116:119], v[226:229], v[76:79]
	s_setprio 0
	s_setprio 1
	v_mfma_f32_16x16x32_bf16 v[148:151], v[128:131], v[152:155], v[148:151]
	v_mfma_f32_16x16x32_bf16 v[148:151], v[132:135], v[156:159], v[148:151]
	v_mfma_f32_16x16x32_bf16 v[144:147], v[136:139], v[152:155], v[144:147]
	v_mfma_f32_16x16x32_bf16 v[144:147], v[140:143], v[156:159], v[144:147]
	v_mfma_f32_16x16x32_bf16 v[96:99], v[136:139], v[160:163], v[96:99]
	v_mfma_f32_16x16x32_bf16 v[96:99], v[140:143], v[164:167], v[96:99]
	v_mfma_f32_16x16x32_bf16 v[100:103], v[128:131], v[160:163], v[100:103]
	v_mfma_f32_16x16x32_bf16 v[100:103], v[132:135], v[164:167], v[100:103]
	v_mfma_f32_16x16x32_bf16 v[84:87], v[128:131], v[200:203], v[84:87]
	v_mfma_f32_16x16x32_bf16 v[84:87], v[132:135], v[204:207], v[84:87]
	v_mfma_f32_16x16x32_bf16 v[80:83], v[136:139], v[200:203], v[80:83]
	v_mfma_f32_16x16x32_bf16 v[80:83], v[140:143], v[204:207], v[80:83]
	v_mfma_f32_16x16x32_bf16 v[64:67], v[136:139], v[208:211], v[64:67]
	v_mfma_f32_16x16x32_bf16 v[64:67], v[140:143], v[226:229], v[64:67]
	v_mfma_f32_16x16x32_bf16 v[68:71], v[128:131], v[208:211], v[68:71]
	v_mfma_f32_16x16x32_bf16 v[68:71], v[132:135], v[226:229], v[68:71]
	s_setprio 0
	s_barrier
	s_add_i32 s69, s69, s14
	v_lshl_add_u64 v[230:231], v[230:231], 0, s[40:41]
	s_mov_b32 m0, s69
	ds_read_b128 v[152:155], v220 offset:49152
	ds_read_b128 v[156:159], v220 offset:50176
	ds_read_b128 v[160:163], v220 offset:51200
	ds_read_b128 v[164:167], v220 offset:52224
	ds_read_b128 v[200:203], v220 offset:53248
	ds_read_b128 v[204:207], v220 offset:54272
	ds_read_b128 v[208:211], v220 offset:55296
	ds_read_b128 v[226:229], v220 offset:56320
	global_load_lds_dwordx4 v[230:231], off
	s_add_i32 m0, s69, 0x2000
	s_add_u32 s80, s80, 0x40080
	v_lshl_add_u64 v[230:231], v[232:233], 0, s[40:41]
	s_addc_u32 s81, s81, 0
	s_add_i32 s69, s73, s14
	global_load_lds_dwordx4 v[230:231], off
	v_lshl_add_u64 v[230:231], s[80:81], 0, v[178:179]
	s_mov_b32 m0, s69
	s_nop 0
	global_load_lds_dwordx4 v[230:231], off
	v_lshl_add_u64 v[230:231], s[80:81], 0, v[182:183]
	s_add_i32 m0, s69, 0x2000
	s_nop 0
	global_load_lds_dwordx4 v[230:231], off
	v_lshl_add_u64 v[230:231], v[234:235], 0, s[40:41]
	s_mov_b32 m0, s57
	s_nop 0
	global_load_lds_dwordx4 v[230:231], off
	v_lshl_add_u64 v[230:231], v[236:237], 0, s[40:41]
	s_mov_b32 m0, s58
	s_nop 0
	global_load_lds_dwordx4 v[230:231], off
	s_waitcnt vmcnt(8)
	s_waitcnt lgkmcnt(0)
	s_barrier
	s_setprio 1
	s_waitcnt lgkmcnt(0)
	v_mfma_f32_16x16x32_bf16 v[60:63], v[112:115], v[152:155], v[60:63]
	v_mfma_f32_16x16x32_bf16 v[60:63], v[116:119], v[156:159], v[60:63]
	v_mfma_f32_16x16x32_bf16 v[56:59], v[120:123], v[152:155], v[56:59]
	v_mfma_f32_16x16x32_bf16 v[56:59], v[124:127], v[156:159], v[56:59]
	v_mfma_f32_16x16x32_bf16 v[40:43], v[120:123], v[160:163], v[40:43]
	v_mfma_f32_16x16x32_bf16 v[40:43], v[124:127], v[164:167], v[40:43]
	v_mfma_f32_16x16x32_bf16 v[44:47], v[112:115], v[160:163], v[44:47]
	v_mfma_f32_16x16x32_bf16 v[44:47], v[116:119], v[164:167], v[44:47]
	v_mfma_f32_16x16x32_bf16 v[28:31], v[112:115], v[200:203], v[28:31]
	v_mfma_f32_16x16x32_bf16 v[28:31], v[116:119], v[204:207], v[28:31]
	v_mfma_f32_16x16x32_bf16 v[24:27], v[120:123], v[200:203], v[24:27]
	v_mfma_f32_16x16x32_bf16 v[24:27], v[124:127], v[204:207], v[24:27]
	v_mfma_f32_16x16x32_bf16 v[8:11], v[120:123], v[208:211], v[8:11]
	v_mfma_f32_16x16x32_bf16 v[8:11], v[124:127], v[226:229], v[8:11]
	v_mfma_f32_16x16x32_bf16 v[12:15], v[112:115], v[208:211], v[12:15]
	v_mfma_f32_16x16x32_bf16 v[12:15], v[116:119], v[226:229], v[12:15]
	s_setprio 0
	s_setprio 1
	v_mfma_f32_16x16x32_bf16 v[52:55], v[128:131], v[152:155], v[52:55]
	v_mfma_f32_16x16x32_bf16 v[52:55], v[132:135], v[156:159], v[52:55]
	v_mfma_f32_16x16x32_bf16 v[48:51], v[136:139], v[152:155], v[48:51]
	v_mfma_f32_16x16x32_bf16 v[48:51], v[140:143], v[156:159], v[48:51]
	v_mfma_f32_16x16x32_bf16 v[32:35], v[136:139], v[160:163], v[32:35]
	v_mfma_f32_16x16x32_bf16 v[32:35], v[140:143], v[164:167], v[32:35]
	v_mfma_f32_16x16x32_bf16 v[36:39], v[128:131], v[160:163], v[36:39]
	v_mfma_f32_16x16x32_bf16 v[36:39], v[132:135], v[164:167], v[36:39]
	v_mfma_f32_16x16x32_bf16 v[20:23], v[128:131], v[200:203], v[20:23]
	v_mfma_f32_16x16x32_bf16 v[20:23], v[132:135], v[204:207], v[20:23]
	v_mfma_f32_16x16x32_bf16 v[16:19], v[136:139], v[200:203], v[16:19]
	v_mfma_f32_16x16x32_bf16 v[16:19], v[140:143], v[204:207], v[16:19]
	v_mfma_f32_16x16x32_bf16 v[0:3], v[136:139], v[208:211], v[0:3]
	v_mfma_f32_16x16x32_bf16 v[0:3], v[140:143], v[226:229], v[0:3]
	v_mfma_f32_16x16x32_bf16 v[4:7], v[128:131], v[208:211], v[4:7]
	v_mfma_f32_16x16x32_bf16 v[4:7], v[132:135], v[226:229], v[4:7]
	s_setprio 0
	s_barrier
	s_add_i32 s68, s68, 2
	s_add_u32 s12, s12, 0x100
	s_addc_u32 s13, s13, 0
	s_add_u32 s35, s35, 0x100
	s_addc_u32 s66, s66, 0
	s_cmp_gt_u32 s68, 13
	s_cbranch_scc0 .LBB0_202
	s_and_b64 vcc, exec, s[42:43]
	s_cbranch_vccz .LBB0_205
	s_barrier
